# diff attention: K/V tiles staged by LDS-DMA into a 3-stage ring (source-side chunk swizzle, counted vmcnt) instead of register staging + ds_write
# speedup vs baseline: 1.0099x; 1.0099x over previous
; DI int opaque_tid() { int t = threadIdx.x; asm volatile("" : "+v"(t)); return t; }
; template <int DV, bool NA> ...
;   const int tid = opaque_tid(), lane = tid & 63;
;   const int h = lane >> 5, r = lane & 31;
;   bf16x8 q[4];
; #pragma unroll
;   for (int ks = 0; ks < 4; ++ks) q[ks] = *(const bf16x8*)(Qp + ks * 16 + h * 8);
; #pragma unroll
;   for (int mv = 0; mv < DV / 32; ++mv)
; #pragma unroll
;     for (int i = 0; i < 16; ++i) o[mv][i] = 0.f;
;   float m_run = -INFINITY, l_run = 0.f;
;   const int lr = tid >> 3, lc = tid & 7;
;   const int wsw = lr * 128 + ((lc ^ ((lr >> 1) & 7)) << 4);
;   u32x4 rk, rv[DV / 64];
;   auto gload = [&](int ti) {
;     const size_t key0 = (size_t)(tile0 + ti) * 64;
;     rk = *(const u32x4*)(Kb + (key0 + lr) * ldk + lc * 8);
; #pragma unroll
;     for (int i = 0; i < DV / 64; ++i) rv[i] = *(const u32x4*)(Vt + (size_t)(lr + 64 * i) * S + key0 + lc * 8);
;   };
;   auto swrite = [&](int st) {
;     char* ks_ = lds + st * ATT_STAGE;
;     *(u32x4*)(ks_ + wsw) = rk;
; #pragma unroll
;     for (int i = 0; i < DV / 64; ++i) *(u32x4*)(ks_ + 8192 + i * 8192 + wsw) = rv[i];
;   };
;   const int pr = (r & 0x13) | ((r & 4) << 1) | ((r & 8) >> 1);
;   const int ksw = (pr >> 1) & 7;
;   const int vsw = (r >> 1) & 7;
;   const int cs_ = NA ? min(max(qc - 8, 0), 48) : 0;
;   __syncthreads();
;   gload(0);
;   swrite(0);
;   if (ntiles > 1) gload(1);
;   __syncthreads();
.LBB0_294:
	v_or_b32_e32 v0, s20, v198
	v_mov_b32_e32 v26, v204
	v_lshlrev_b64 v[2:3], 1, v[0:1]
	v_lshl_add_u64 v[4:5], v[162:163], 0, v[2:3]
	v_bfe_u32 v27, v26, 5, 1
	v_lshl_add_u64 v[2:3], v[160:161], 0, v[2:3]
	v_lshlrev_b32_e32 v0, 4, v27
	v_ashrrev_i32_e32 v14, 3, v26
	v_lshlrev_b32_e32 v28, 4, v26
	v_lshl_add_u64 v[4:5], v[4:5], 0, v[0:1]
	v_ashrrev_i32_e32 v15, 31, v14
	v_mad_i64_i32 v[2:3], s[22:23], v14, s96, v[2:3]
	v_and_b32_e32 v0, 0x70, v28
	v_add_u32_e32 v10, 64, v14
	v_lshl_add_u64 v[16:17], v[2:3], 0, v[0:1]
	v_lshlrev_b64 v[2:3], v176, v[14:15]
	v_ashrrev_i32_e32 v11, 31, v10
	v_lshlrev_b64 v[18:19], 1, v[2:3]
	v_lshlrev_b64 v[10:11], v176, v[10:11]
	v_lshl_add_u64 v[2:3], v[164:165], 0, v[18:19]
	v_lshlrev_b64 v[22:23], 1, v[10:11]
	global_load_dwordx4 v[124:127], v[4:5], off
	global_load_dwordx4 v[120:123], v[4:5], off offset:32
	global_load_dwordx4 v[116:119], v[4:5], off offset:64
	global_load_dwordx4 v[112:115], v[4:5], off offset:96
	s_barrier
	v_lshl_add_u64 v[20:21], v[2:3], 0, v[0:1]
	global_load_dwordx4 v[2:5], v[16:17], off offset:1024
	global_load_dwordx4 v[6:9], v[20:21], off
	v_lshl_add_u64 v[10:11], v[164:165], 0, v[22:23]
	v_lshl_add_u64 v[24:25], v[10:11], 0, v[0:1]
	v_add_co_u32_e32 v16, vcc, s97, v16
	global_load_dwordx4 v[10:13], v[24:25], off
	s_nop 0
	v_addc_co_u32_e32 v17, vcc, 0, v17, vcc
	global_load_dwordx4 v[132:135], v[20:21], off offset:128
	global_load_dwordx4 v[128:131], v[16:17], off offset:1024
	global_load_dwordx4 v[136:139], v[24:25], off offset:128
	v_lshlrev_b32_e32 v15, 1, v26
	v_lshrrev_b32_e32 v20, 1, v26
	v_lshrrev_b32_e32 v16, 5, v26
	v_and_b32_e32 v17, 19, v26
	v_bfe_u32 v21, v26, 1, 3
	v_lshlrev_b32_e32 v24, 7, v26
	v_xor_b32_e32 v26, v28, v26
	v_and_b32_e32 v28, 8, v15
	v_and_b32_e32 v20, 4, v20
	v_bitop3_b32 v16, v16, v21, 1 bitop3:0x6c
	v_or3_b32 v17, v28, v17, v20
	v_lshlrev_b32_e32 v25, 7, v14
	v_and_b32_e32 v178, 0xf80, v24
	v_or_b32_e32 v24, 4, v27
	v_or_b32_e32 v29, 2, v27
	v_or_b32_e32 v30, 6, v27
	v_bitop3_b32 v31, v27, v21, 2 bitop3:0x36
	v_bitop3_b32 v32, v27, v21, 4 bitop3:0x36
	v_bitop3_b32 v21, v27, v21, 6 bitop3:0x36
	v_lshlrev_b32_e32 v195, 4, v16
	v_lshrrev_b32_e32 v16, 1, v17
	v_mad_i64_i32 v[14:15], s[22:23], v14, s96, 0
	v_and_or_b32 v203, v26, s66, v25
	v_lshlrev_b32_e32 v179, 4, v21
	v_lshlrev_b32_e32 v228, 7, v17
	v_bitop3_b32 v20, v16, v27, 7 bitop3:0x6c
	v_bitop3_b32 v21, v16, v29, 7 bitop3:0x6c
	v_bitop3_b32 v24, v16, v24, 7 bitop3:0x6c
	v_bitop3_b32 v25, v16, v30, 7 bitop3:0x6c
	v_lshl_add_u64 v[16:17], v[0:1], 0, v[18:19]
	v_or_b32_e32 v14, v14, v0
	v_lshl_add_u64 v[170:171], v[166:167], 0, v[16:17]
	v_lshl_add_u64 v[16:17], v[0:1], 0, v[22:23]
	v_add_u32_e32 v0, s20, v198
	s_waitcnt vmcnt(18)
	v_lshlrev_b32_e32 v183, 4, v31
	v_lshlrev_b32_e32 v181, 4, v32
	v_lshlrev_b32_e32 v229, 4, v20
	v_lshlrev_b32_e32 v202, 4, v21
	v_lshlrev_b32_e32 v201, 4, v24
	v_lshlrev_b32_e32 v200, 4, v25
	v_lshl_add_u64 v[172:173], v[166:167], 0, v[16:17]
	v_mov_b32_e32 v180, 0
	v_mov_b32_e32 v182, 0xff800000
	s_mov_b64 s[20:21], 0
	s_mov_b32 s31, 0
	s_waitcnt vmcnt(5)
	ds_write_b128 v203, v[2:5]
	s_waitcnt vmcnt(4)
	ds_write_b128 v203, v[6:9] offset:8192
	s_waitcnt vmcnt(3)
	ds_write_b128 v203, v[10:13] offset:16384
	v_lshl_add_u64 v[2:3], v[0:1], 1, v[14:15]
	v_mov_b32_e32 v14, v1
	v_mov_b32_e32 v15, v1
	v_lshl_add_u64 v[174:175], v[168:169], 0, v[2:3]
	v_mov_b32_e32 v0, v1
	v_mov_b32_e32 v2, v1
	v_mov_b32_e32 v3, v1
	v_mov_b32_e32 v4, v1
	v_mov_b32_e32 v5, v1
	v_mov_b32_e32 v6, v1
	v_mov_b32_e32 v7, v1
	v_mov_b32_e32 v8, v1
	v_mov_b32_e32 v9, v1
	v_mov_b32_e32 v10, v1
	v_mov_b32_e32 v11, v1
	v_mov_b32_e32 v12, v1
	v_mov_b32_e32 v13, v1
	v_mov_b64_e32 v[30:31], v[14:15]
	v_mov_b64_e32 v[46:47], v[14:15]
	v_mov_b64_e32 v[62:63], v[14:15]
	v_mov_b64_e32 v[78:79], v[14:15]
	v_mov_b64_e32 v[28:29], v[12:13]
	v_mov_b64_e32 v[26:27], v[10:11]
	v_mov_b64_e32 v[24:25], v[8:9]
	v_mov_b64_e32 v[22:23], v[6:7]
	v_mov_b64_e32 v[20:21], v[4:5]
	v_mov_b64_e32 v[18:19], v[2:3]
	v_mov_b64_e32 v[16:17], v[0:1]
	v_mov_b64_e32 v[44:45], v[12:13]
	v_mov_b64_e32 v[42:43], v[10:11]
	v_mov_b64_e32 v[40:41], v[8:9]
	v_mov_b64_e32 v[38:39], v[6:7]
	v_mov_b64_e32 v[36:37], v[4:5]
	v_mov_b64_e32 v[34:35], v[2:3]
	v_mov_b64_e32 v[32:33], v[0:1]
	v_mov_b64_e32 v[60:61], v[12:13]
	v_mov_b64_e32 v[58:59], v[10:11]
	v_mov_b64_e32 v[56:57], v[8:9]
	v_mov_b64_e32 v[54:55], v[6:7]
	v_mov_b64_e32 v[52:53], v[4:5]
	v_mov_b64_e32 v[50:51], v[2:3]
	v_mov_b64_e32 v[48:49], v[0:1]
	v_mov_b64_e32 v[76:77], v[12:13]
	v_mov_b64_e32 v[74:75], v[10:11]
	v_mov_b64_e32 v[72:73], v[8:9]
	v_mov_b64_e32 v[70:71], v[6:7]
	v_mov_b64_e32 v[68:69], v[4:5]
	v_mov_b64_e32 v[66:67], v[2:3]
	v_mov_b64_e32 v[64:65], v[0:1]
	v_mov_b32_e32 v182, 0
	s_mov_b32 s100, 0xff800000
	v_mov_b32_e32 v234, 0
	v_mov_b32_e32 v235, 0
	v_mov_b32_e32 v236, 0
	v_mov_b32_e32 v237, 0
	v_mov_b32_e32 v238, 0
	v_mov_b32_e32 v239, 0
	v_mov_b32_e32 v240, 0
	v_mov_b32_e32 v241, 0
	v_mov_b32_e32 v242, 0
	v_mov_b32_e32 v243, 0
	v_mov_b32_e32 v244, 0
	v_mov_b32_e32 v245, 0
	v_mov_b32_e32 v246, 0
	v_mov_b32_e32 v247, 0
	v_mov_b32_e32 v248, 0
	v_mov_b32_e32 v249, 0
	v_add_u32_e32 v159, 0x6000, v203
	s_waitcnt vmcnt(1)
	ds_write_b128 v159, v[128:131]
	ds_write_b128 v159, v[132:135] offset:8192
	s_waitcnt vmcnt(0)
	ds_write_b128 v159, v[136:139] offset:16384
	v_and_b32_e32 v231, 7, v204
	v_bfe_u32 v232, v204, 4, 3
	v_xor_b32_e32 v232, v232, v231
	v_sub_u32_e32 v232, v232, v231
	v_lshlrev_b32_e32 v232, 4, v232
	v_ashrrev_i32_e32 v233, 31, v232
	v_lshl_add_u64 v[174:175], v[174:175], 0, v[232:233]
	v_lshl_add_u64 v[170:171], v[170:171], 0, v[232:233]
	v_lshl_add_u64 v[172:173], v[172:173], 0, v[232:233]
	v_readfirstlane_b32 s23, v185
	v_readfirstlane_b32 s101, v204
	s_mov_b32 s30, 0xc000
	s_mov_b32 s22, 0
	s_lshr_b32 s101, s101, 6
	s_lshl_b32 s101, s101, 10
	s_waitcnt lgkmcnt(0)
	s_barrier
	s_branch .LBB0_296
; template <int DV, bool NA> ...
;     ...
;   for (int ti = 0; ti < ntiles; ++ti) {
;     if (ti + 1 < ntiles) {
;       swrite((ti + 1) & 1);
;       if (ti + 2 < ntiles) gload(ti + 2);
;     }
;     const char* st = lds + (ti & 1) * ATT_STAGE;
;     const bool active = !NA || ((tile0 + ti) >= wlo && (tile0 + ti) <= whi);
;     if (active) {
;       f32x16 s0, s1;
; #pragma unroll
;       for (int i = 0; i < 16; ++i) { s0[i] = 0.f; s1[i] = 0.f; }
;       {
;         bf16x8 ka[4], kb_[4];
; #pragma unroll
;         for (int ks = 0; ks < 4; ++ks) {
;           const int co = ((2 * ks + h) ^ ksw) << 4;
;           ka[ks] = *(const bf16x8*)(st + pr * 128 + co);
;           kb_[ks] = *(const bf16x8*)(st + (32 + pr) * 128 + co);
;         }
;         asm volatile("" ::: "memory");
; #pragma unroll
;         for (int ks = 0; ks < 4; ++ks) {
;           s0 = MFMA(ka[ks], q[ks], s0);
;           s1 = MFMA(kb_[ks], q[ks], s1);
;         }
;       }
;       bf16x8 vf0[2][DV / 32];
; #pragma unroll
;       for (int c2 = 0; c2 < 2; ++c2) {
;         const int co = ((2 * c2 + h) ^ vsw) << 4;
; #pragma unroll
;         for (int mv = 0; mv < DV / 32; ++mv) vf0[c2][mv] = *(const bf16x8*)(st + 8192 + (mv * 32 + r) * 128 + co);
;       }
;       asm volatile("" ::: "memory");
;     ...
;       float ls = 0.f;
; #pragma unroll
;       for (int e = 0; e < 32; ++e) { t[e] = fexp2(t[e] - m_run); ls += t[e]; }
;       l_run += ls;
;       bf16x8 pf[2][2];
; #pragma unroll
;       for (int kb = 0; kb < 2; ++kb)
; #pragma unroll
;         for (int c2 = 0; c2 < 2; ++c2) {
;           const int e0 = kb * 16 + c2 * 8;
;           u32x4 pw = {pk_bf16(t[e0], t[e0 + 1]), pk_bf16(t[e0 + 2], t[e0 + 3]), pk_bf16(t[e0 + 4], t[e0 + 5]), pk_bf16(t[e0 + 6], t[e0 + 7])};
;           pf[kb][c2] = __builtin_bit_cast(bf16x8, pw);
;         }
;       bf16x8 vf1[2][DV / 32];
; #pragma unroll
;       for (int c2 = 0; c2 < 2; ++c2) {
;         const int co = ((4 + 2 * c2 + h) ^ vsw) << 4;
; #pragma unroll
;         for (int mv = 0; mv < DV / 32; ++mv) vf1[c2][mv] = *(const bf16x8*)(st + 8192 + (mv * 32 + r) * 128 + co);
;       }
;       asm volatile("" ::: "memory");
; #pragma unroll
;       for (int c2 = 0; c2 < 2; ++c2)
; #pragma unroll
;         for (int mv = 0; mv < DV / 32; ++mv) o[mv] = MFMA(vf0[c2][mv], pf[0][c2], o[mv]);
; #pragma unroll
;       for (int c2 = 0; c2 < 2; ++c2)
; #pragma unroll
.LBB0_296:
	s_add_i32 s29, s31, 1
	s_add_i32 vcc_lo, s31, 2
	s_cmp_lt_u32 vcc_lo, s23
	s_cbranch_scc0 .Ldf_nodma
	s_add_u32 m0, s30, s101
	s_nop 0
	global_load_lds_dwordx4 v[174:175], off
	s_add_u32 m0, m0, 0x2000
	v_lshl_add_u64 v[174:175], v[174:175], 0, s[82:83]
	global_load_lds_dwordx4 v[170:171], off
	s_add_u32 m0, m0, 0x2000
	v_lshl_add_u64 v[170:171], v[170:171], 0, s[4:5]
	global_load_lds_dwordx4 v[172:173], off
	v_lshl_add_u64 v[172:173], v[172:173], 0, s[4:5]
	s_branch .Ldf_dmadone
.Ldf_nodma:
	s_waitcnt vmcnt(0)
.Ldf_dmadone:
	v_add_u32_e32 v158, s22, v228
	v_add_u32_e32 v159, v158, v229
	ds_read_b128 v[0:3], v159
	ds_read_b128 v[4:7], v159 offset:4096
	v_add_u32_e32 v159, v158, v202
	ds_read_b128 v[8:11], v159
	ds_read_b128 v[12:15], v159 offset:4096
	v_add3_u32 v210, s22, v195, v178
	s_waitcnt lgkmcnt(2)
	v_mfma_f32_32x32x16_bf16 v[96:111], v[0:3], v[124:127], v[234:249]
	v_mfma_f32_32x32x16_bf16 v[80:95], v[4:7], v[124:127], v[234:249]
	v_add_u32_e32 v159, v158, v201
	ds_read_b128 v[0:3], v159
	ds_read_b128 v[4:7], v159 offset:4096
	s_waitcnt lgkmcnt(2)
	v_mfma_f32_32x32x16_bf16 v[96:111], v[8:11], v[120:123], v[96:111]
	v_mfma_f32_32x32x16_bf16 v[80:95], v[12:15], v[120:123], v[80:95]
	v_add_u32_e32 v159, v158, v200
	ds_read_b128 v[8:11], v159
	ds_read_b128 v[12:15], v159 offset:4096
	ds_read_b128 v[140:143], v210 offset:8192
	ds_read_b128 v[144:147], v210 offset:12288
	ds_read_b128 v[148:151], v210 offset:16384
	ds_read_b128 v[152:155], v210 offset:20480
	v_add3_u32 v230, s22, v183, v178
	s_waitcnt lgkmcnt(6)
	v_mfma_f32_32x32x16_bf16 v[96:111], v[0:3], v[116:119], v[96:111]
	v_mfma_f32_32x32x16_bf16 v[80:95], v[4:7], v[116:119], v[80:95]
	s_waitcnt lgkmcnt(4)
	v_mfma_f32_32x32x16_bf16 v[96:111], v[8:11], v[112:115], v[96:111]
	v_mfma_f32_32x32x16_bf16 v[80:95], v[12:15], v[112:115], v[80:95]
	ds_read_b128 v[0:3], v230 offset:8192
	ds_read_b128 v[4:7], v230 offset:12288
	ds_read_b128 v[8:11], v230 offset:16384
	ds_read_b128 v[12:15], v230 offset:20480
	v_cmp_eq_u32_e32 vcc, s29, v177
	v_add3_u32 v210, s22, v181, v178
	v_add3_u32 v230, s22, v179, v178
	s_or_b64 s[20:21], vcc, s[20:21]
.Ldf_exps:
	s_nop 2
	v_exp_f32_e32 v96, v96
	v_exp_f32_e32 v97, v97
	v_exp_f32_e32 v98, v98
	v_exp_f32_e32 v99, v99
	v_exp_f32_e32 v100, v100
	v_exp_f32_e32 v101, v101
	v_exp_f32_e32 v102, v102
	v_exp_f32_e32 v103, v103
	v_exp_f32_e32 v104, v104
	v_exp_f32_e32 v105, v105
	v_add_f32_e32 v156, v96, v98
	v_add_f32_e32 v157, v97, v99
	v_exp_f32_e32 v106, v106
	v_exp_f32_e32 v107, v107
	v_add_f32_e32 v156, v156, v100
	v_add_f32_e32 v157, v157, v101
	v_exp_f32_e32 v108, v108
	v_exp_f32_e32 v109, v109
	v_add_f32_e32 v156, v156, v102
	v_add_f32_e32 v157, v157, v103
	v_exp_f32_e32 v110, v110
	v_exp_f32_e32 v111, v111
	v_add_f32_e32 v156, v156, v104
	v_add_f32_e32 v157, v157, v105
	v_exp_f32_e32 v80, v80
	v_exp_f32_e32 v81, v81
	v_add_f32_e32 v156, v156, v106
	v_add_f32_e32 v157, v157, v107
	v_exp_f32_e32 v82, v82
	v_exp_f32_e32 v83, v83
	v_add_f32_e32 v156, v156, v108
	v_add_f32_e32 v157, v157, v109
	v_exp_f32_e32 v84, v84
	v_exp_f32_e32 v85, v85
	v_add_f32_e32 v156, v156, v110
	v_add_f32_e32 v157, v157, v111
	v_exp_f32_e32 v86, v86
	v_exp_f32_e32 v87, v87
	v_add_f32_e32 v156, v156, v80
	v_add_f32_e32 v157, v157, v81
	v_exp_f32_e32 v88, v88
	v_exp_f32_e32 v89, v89
	v_add_f32_e32 v156, v156, v82
	v_add_f32_e32 v157, v157, v83
	v_exp_f32_e32 v90, v90
	v_exp_f32_e32 v91, v91
	v_add_f32_e32 v156, v156, v84
	v_add_f32_e32 v157, v157, v85
	v_exp_f32_e32 v92, v92
	v_exp_f32_e32 v93, v93
	v_add_f32_e32 v156, v156, v86
	v_add_f32_e32 v157, v157, v87
	v_exp_f32_e32 v94, v94
	v_exp_f32_e32 v95, v95
	v_add_f32_e32 v156, v156, v88
	v_add_f32_e32 v157, v157, v89
	v_add_f32_e32 v156, v156, v90
	v_add_f32_e32 v157, v157, v91
	v_add_f32_e32 v156, v156, v92
	v_add_f32_e32 v157, v157, v93
	v_add_f32_e32 v156, v156, v94
	v_add_f32_e32 v157, v157, v95
	v_add_f32_e32 v156, v156, v157
	v_cmp_lt_f32_e32 vcc, s100, v156
	s_cbranch_vccnz .Ldf_fix
	v_add_f32_e32 v180, v180, v156
	v_cvt_pk_bf16_f32 v96, v96, v97
	v_cvt_pk_bf16_f32 v97, v98, v99
	v_cvt_pk_bf16_f32 v98, v100, v101
	v_cvt_pk_bf16_f32 v99, v102, v103
	s_waitcnt lgkmcnt(4)
	s_nop 0
	v_mfma_f32_32x32x16_bf16 v[64:79], v[140:143], v[96:99], v[64:79]
	v_cvt_pk_bf16_f32 v104, v104, v105
	v_mfma_f32_32x32x16_bf16 v[48:63], v[144:147], v[96:99], v[48:63]
	v_cvt_pk_bf16_f32 v105, v106, v107
	v_mfma_f32_32x32x16_bf16 v[32:47], v[148:151], v[96:99], v[32:47]
	v_cvt_pk_bf16_f32 v106, v108, v109
	v_mfma_f32_32x32x16_bf16 v[16:31], v[152:155], v[96:99], v[16:31]
	v_cvt_pk_bf16_f32 v107, v110, v111
	ds_read_b128 v[140:143], v210 offset:8192
	ds_read_b128 v[144:147], v210 offset:12288
	ds_read_b128 v[148:151], v210 offset:16384
	ds_read_b128 v[152:155], v210 offset:20480
	s_waitcnt lgkmcnt(4)
	v_mfma_f32_32x32x16_bf16 v[64:79], v[0:3], v[104:107], v[64:79]
	v_cvt_pk_bf16_f32 v80, v80, v81
	v_mfma_f32_32x32x16_bf16 v[48:63], v[4:7], v[104:107], v[48:63]
	v_cvt_pk_bf16_f32 v81, v82, v83
	v_mfma_f32_32x32x16_bf16 v[32:47], v[8:11], v[104:107], v[32:47]
	v_cvt_pk_bf16_f32 v82, v84, v85
	v_mfma_f32_32x32x16_bf16 v[16:31], v[12:15], v[104:107], v[16:31]
	v_cvt_pk_bf16_f32 v83, v86, v87
	ds_read_b128 v[0:3], v230 offset:8192
	ds_read_b128 v[4:7], v230 offset:12288
	ds_read_b128 v[8:11], v230 offset:16384
	ds_read_b128 v[12:15], v230 offset:20480
	s_waitcnt lgkmcnt(4)
	v_mfma_f32_32x32x16_bf16 v[64:79], v[140:143], v[80:83], v[64:79]
	v_cvt_pk_bf16_f32 v88, v88, v89
	v_mfma_f32_32x32x16_bf16 v[48:63], v[144:147], v[80:83], v[48:63]
	v_cvt_pk_bf16_f32 v89, v90, v91
	v_mfma_f32_32x32x16_bf16 v[32:47], v[148:151], v[80:83], v[32:47]
	v_cvt_pk_bf16_f32 v90, v92, v93
	v_mfma_f32_32x32x16_bf16 v[16:31], v[152:155], v[80:83], v[16:31]
	v_cvt_pk_bf16_f32 v91, v94, v95
	s_waitcnt lgkmcnt(0)
	s_nop 0
	v_mfma_f32_32x32x16_bf16 v[64:79], v[0:3], v[88:91], v[64:79]
	v_mfma_f32_32x32x16_bf16 v[48:63], v[4:7], v[88:91], v[48:63]
	v_mfma_f32_32x32x16_bf16 v[32:47], v[8:11], v[88:91], v[32:47]
	v_mfma_f32_32x32x16_bf16 v[16:31], v[12:15], v[88:91], v[16:31]
	s_add_u32 vcc_lo, s22, s30
	s_mov_b32 s30, s22
	s_sub_u32 s22, 0x12000, vcc_lo
	v_mov_b32_e32 v0, s22
	v_mov_b32_e32 v1, 0
	s_mov_b32 s31, s29
	s_waitcnt vmcnt(3)
	s_waitcnt lgkmcnt(0)
	s_barrier
	s_andn2_b64 exec, exec, s[20:21]
	s_cbranch_execnz .LBB0_296
	v_readfirstlane_b32 s101, v204
	s_nop 0
	s_lshr_b32 s101, s101, 8
	s_branch .LBB0_300
